# adds: NA tile loop compiler vmcnt(0) relaxed to lgkmcnt; LRU unit staging loads prefetched
# baseline (speedup 1.0000x reference)
; template <int MODE, int CH = -1>
; DI void lru_group_unit(KP p, int l, int g, int n, char* ldsc) {
;     ...
;     for (int q = lane; q < 35 * 8; q += 64) {
;       const int tt = q >> 3, pc = q & 7, t = t0 + tt - 2;
;       u32x4 v = {0u, 0u, 0u, 0u};
;       if (t >= 0 && t < L) v = *(const u32x4*)(p->P + (size_t)(row0 + tt - 2) * INC + n * 64 + pc * 8);
;       *(u32x4*)(xs + tt * 64 + pc * 8) = v;
;     }
.LBB0_332:
	s_or_b64 exec, exec, s[6:7]
	s_ashr_i32 s20, s16, 2
	s_lshl_b32 s3, s20, 8
	v_and_b32_e32 v2, 7, v43
	v_lshrrev_b32_e32 v3, 3, v41
	s_mul_i32 s1, s0, 0x2400
	s_lshl_b32 s2, s0, 5
	s_and_b32 s4, s3, 0x1f00
	v_lshlrev_b32_e32 v0, 3, v2
	v_lshlrev_b32_e32 v2, 4, v2
	v_add_u32_e32 v4, -2, v3
	v_lshlrev_b32_e32 v3, 7, v3
	s_add_i32 s3, s2, s3
	v_or3_b32 v2, s1, v3, v2
	s_add_i32 s2, s2, s4
	v_lshlrev_b32_e32 v44, 3, v43
	v_mov_b32_e32 v35, v1
	v_or_b32_e32 v6, 0xffffffc0, v41
	v_add_u32_e32 v7, s3, v4
	v_add_u32_e32 v8, s94, v2
	v_add_u32_e32 v9, s2, v4
	s_mov_b64 s[6:7], 0
	v_lshlrev_b32_e32 v0, 1, v0
	s_load_dwordx2 s[2:3], s[10:11], 0xf8
	s_waitcnt lgkmcnt(0)
	v_mov_b64_e32 v[252:253], s[2:3]
	v_lshl_add_u64 v[252:253], v[34:35], 1, v[252:253]
	v_lshl_add_u64 v[250:251], v[252:253], 0, v[0:1]
	v_mad_i64_i32 v[252:253], s[4:5], v7, s45, v[250:251]
	global_load_dwordx4 v[244:247], v[252:253], off
	v_add_u32_e32 v248, 8, v7
	v_mad_i64_i32 v[252:253], s[4:5], v248, s45, v[250:251]
	global_load_dwordx4 v[244:247], v[252:253], off
	v_add_u32_e32 v248, 16, v7
	v_mad_i64_i32 v[252:253], s[4:5], v248, s45, v[250:251]
	global_load_dwordx4 v[244:247], v[252:253], off
	v_add_u32_e32 v248, 24, v7
	v_mad_i64_i32 v[252:253], s[4:5], v248, s45, v[250:251]
	global_load_dwordx4 v[244:247], v[252:253], off
	v_add_u32_e32 v248, 32, v7
	v_mad_i64_i32 v[252:253], s[4:5], v248, s45, v[250:251]
	global_load_dwordx4 v[244:247], v[252:253], off
	s_branch .LBB0_334

; #define MFMA32(a, b, c) __builtin_amdgcn_mfma_f32_32x32x16_bf16((a), (b), (c), 0, 0, 0)
; #define ASCHED __builtin_amdgcn_sched_barrier(0)
; template <int DV, bool LOCAL>
; DI void attn_tile(const bf16x8 (&qf)[4], const lds_u8* Kb, const lds_u8* Vb, const int (&ko)[4], const int (&vo)[4], f32x16 (&o)[DV / 32], float& m, float& l, int hh,
;                   const float* rpbs, int drow, int cq, int c0) {
;     ...
;   f32x16 st[2];
;   {
;     bf16x8 kf[2][4];
; #pragma unroll
;     for (int t = 0; t < 2; ++t)
; #pragma unroll
;       for (int ks = 0; ks < 4; ++ks) kf[t][ks] = *(const lds_bf16x8*)(Kb + ko[ks] + t * 4096);
;     ASCHED;
; #pragma unroll
;     for (int t = 0; t < 2; ++t) {
;       f32x16 s;
; #pragma unroll
;       for (int i = 0; i < 16; ++i) s[i] = 0.f;
; #pragma unroll
;       for (int ks = 0; ks < 4; ++ks) s = MFMA32(kf[t][ks], qf[ks], s);
;       st[t] = s;
;     }
;   }
;   bf16x8 va[2][ND];
; #pragma unroll
;   for (int s2 = 0; s2 < 2; ++s2)
; #pragma unroll
;     for (int d = 0; d < ND; ++d) va[s2][d] = *(const lds_bf16x8*)(Vb + vo[s2] + d * 4096);
.LBB0_506:
	s_add_i32 s41, s0, s54
	s_add_i32 s41, s41, -8
	s_cmp_ge_i32 s41, s72
	s_cselect_b64 s[52:53], -1, 0
	s_cmp_lt_i32 s41, s40
	s_cselect_b64 vcc, -1, 0
	s_and_b64 s[52:53], s[52:53], vcc
	v_mov_b64_e32 v[64:65], v[32:33]
	s_andn2_b64 vcc, exec, s[52:53]
	v_mov_b64_e32 v[62:63], v[30:31]
	v_mov_b64_e32 v[60:61], v[28:29]
	v_mov_b64_e32 v[58:59], v[26:27]
	v_mov_b64_e32 v[56:57], v[24:25]
	v_mov_b64_e32 v[54:55], v[22:23]
	v_mov_b64_e32 v[52:53], v[20:21]
	v_mov_b64_e32 v[50:51], v[18:19]
	v_mov_b64_e32 v[48:49], v[16:17]
	v_mov_b64_e32 v[46:47], v[14:15]
	v_mov_b64_e32 v[44:45], v[12:13]
	v_mov_b64_e32 v[42:43], v[10:11]
	v_mov_b64_e32 v[40:41], v[8:9]
	v_mov_b64_e32 v[38:39], v[6:7]
	v_mov_b64_e32 v[36:37], v[4:5]
	v_mov_b64_e32 v[34:35], v[2:3]
	v_mov_b32_e32 v148, v147
	v_mov_b32_e32 v200, v146
	s_cbranch_vccnz .LBB0_574
	v_add_u32_e32 v0, s55, v99
	v_add_u32_e32 v46, s55, v101
	v_add_u32_e32 v50, s55, v106
	v_add_u32_e32 v51, s55, v107
	ds_read_b128 v[34:37], v0
	ds_read_b128 v[38:41], v0 offset:4096
	ds_read_b128 v[42:45], v46
	ds_read_b128 v[82:85], v46 offset:4096
	ds_read_b128 v[46:49], v50
	ds_read_b128 v[86:89], v50 offset:4096
	ds_read_b128 v[90:93], v51
	ds_read_b128 v[94:97], v51 offset:4096
	s_waitcnt lgkmcnt(0)
	v_mfma_f32_32x32x16_bf16 v[50:65], v[34:37], v[74:77], 0
	v_add_u32_e32 v0, s55, v108
	v_mfma_f32_32x32x16_bf16 v[50:65], v[42:45], v[66:69], v[50:65]
	v_mfma_f32_32x32x16_bf16 v[50:65], v[46:49], v[70:73], v[50:65]
	v_mfma_f32_32x32x16_bf16 v[34:49], v[38:41], v[74:77], 0
	v_mfma_f32_32x32x16_bf16 v[34:49], v[82:85], v[66:69], v[34:49]
	v_mfma_f32_32x32x16_bf16 v[34:49], v[86:89], v[70:73], v[34:49]
	v_mfma_f32_32x32x16_bf16 v[50:65], v[90:93], v[78:81], v[50:65]
	v_mfma_f32_32x32x16_bf16 v[34:49], v[94:97], v[78:81], v[34:49]
	ds_read_b128 v[94:97], v0 offset:8192
	ds_read_b128 v[90:93], v0 offset:12288
	v_add_u32_e32 v0, s55, v109
	ds_read_b128 v[86:89], v0 offset:8192
	ds_read_b128 v[82:85], v0 offset:12288
	v_add_u32_e32 v148, s65, v145
	v_add_u32_e32 v0, s65, v144
	v_add_u32_e32 v150, s65, v143
	v_add_u32_e32 v149, s65, v141
	v_add_u32_e32 v152, s65, v140
	v_add_u32_e32 v151, s65, v139
	v_add_u32_e32 v154, s65, v138
	v_add_u32_e32 v153, s65, v137
	v_add_u32_e32 v156, s65, v136
	v_add_u32_e32 v155, s65, v135
	v_add_u32_e32 v191, s65, v134
	v_add_u32_e32 v157, s65, v133
	v_add_u32_e32 v193, s65, v132
	v_add_u32_e32 v192, s65, v131
	v_add_u32_e32 v195, s65, v129
	v_add_u32_e32 v194, s65, v128
	v_add_u32_e32 v197, s65, v127
	v_add_u32_e32 v196, s65, v126
	v_add_u32_e32 v199, s65, v125
	v_add_u32_e32 v198, s65, v124
	v_add_u32_e32 v202, s65, v123
	v_add_u32_e32 v201, s65, v122
	v_add_u32_e32 v204, s65, v121
	v_add_u32_e32 v203, s65, v120
	v_add_u32_e32 v206, s65, v119
	v_add_u32_e32 v205, s65, v118
	v_add_u32_e32 v208, s65, v117
	v_add_u32_e32 v207, s65, v116
	v_add_u32_e32 v210, s65, v115
	v_add_u32_e32 v209, s65, v114
	v_add_u32_e32 v212, s65, v113
	v_add_u32_e32 v211, s65, v112
	ds_read_b32 v148, v148
	ds_read_b32 v0, v0
	ds_read_b32 v150, v150
	ds_read_b32 v149, v149
	ds_read_b32 v152, v152
	ds_read_b32 v151, v151
	ds_read_b32 v154, v154
	ds_read_b32 v153, v153
	ds_read_b32 v156, v156
	ds_read_b32 v155, v155
	ds_read_b32 v191, v191
	ds_read_b32 v157, v157
	ds_read_b32 v193, v193
	ds_read_b32 v192, v192
	ds_read_b32 v195, v195
	ds_read_b32 v194, v194
	ds_read_b32 v197, v197
	ds_read_b32 v196, v196
	ds_read_b32 v199, v199
	ds_read_b32 v198, v198
	ds_read_b32 v202, v202
	ds_read_b32 v201, v201
	ds_read_b32 v204, v204
	ds_read_b32 v203, v203
	ds_read_b32 v206, v206
	ds_read_b32 v205, v205
	ds_read_b32 v208, v208
	ds_read_b32 v207, v207
	ds_read_b32 v210, v210
	ds_read_b32 v209, v209
	ds_read_b32 v212, v212
	ds_read_b32 v211, v211
	v_mov_b32_e32 v216, 0xf149f2ca
	s_waitcnt lgkmcnt(0)
; DI float xhalf_max(float v) { const auto r = __builtin_amdgcn_permlane32_swap(__float_as_uint(v), __float_as_uint(v), false, false); return fmaxf(__uint_as_float(r[0]), __uint_as_float(r[1])); }
; template <int DV, bool LOCAL>
; DI void attn_tile(const bf16x8 (&qf)[4], const lds_u8* Kb, const lds_u8* Vb, const int (&ko)[4], const int (&vo)[4], f32x16 (&o)[DV / 32], float& m, float& l, int hh,
;                   const float* rpbs, int drow, int cq, int c0) {
;     ...
;       for (int i = 0; i < 16; ++i) {
;         const int ck = 32 * t + 16 * (i >> 3) + 8 * hh + (i & 7);
;         const int dc = ck - cq + 15;
;         const bool ok = (ck >= c0) && (ck < c0 + 16);
;         const int dcc = dc < 0 ? 0 : (dc > 30 ? 30 : dc);
;         const float z = ok ? __builtin_fmaf(st[t][i], QK_C, rpbs[drow * 31 + dcc]) : -1.0e30f;
;         st[t][i] = z; mx = fmaxf(mx, z);
;       }
;   } else {
; #pragma unroll
;     for (int t = 0; t < 2; ++t)
; #pragma unroll
;       for (int i = 0; i < 16; ++i) mx = fmaxf(mx, st[t][i]);
;     mx *= QK_C;
;   }
;   mx = xhalf_max(mx);
;   if (!__all(mx <= m + 8.0f)) {
;     const float mn = fmaxf(m, mx);
;     const float alpha = __builtin_amdgcn_exp2f(m - mn);
;     m = mn; l *= alpha;
; #pragma unroll
;     for (int d = 0; d < ND; ++d) o[d] *= alpha;
;   }
	v_fmac_f32_e32 v148, 0x3e38aa3b, v50
	v_cndmask_b32_e64 v148, v216, v148, s[4:5]
	v_fmac_f32_e32 v0, 0x3e38aa3b, v51
	v_cndmask_b32_e64 v0, v216, v0, s[6:7]
	v_fmac_f32_e32 v150, 0x3e38aa3b, v52
	v_cndmask_b32_e64 v150, v216, v150, s[8:9]
	v_fmac_f32_e32 v149, 0x3e38aa3b, v53
	v_cndmask_b32_e64 v149, v216, v149, s[10:11]
	v_fmac_f32_e32 v152, 0x3e38aa3b, v54
	v_cndmask_b32_e64 v152, v216, v152, s[12:13]
	v_fmac_f32_e32 v151, 0x3e38aa3b, v55
	v_cndmask_b32_e64 v151, v216, v151, s[14:15]
	v_fmac_f32_e32 v154, 0x3e38aa3b, v56
	v_cndmask_b32_e64 v154, v216, v154, s[16:17]
	v_fmac_f32_e32 v153, 0x3e38aa3b, v57
	v_cndmask_b32_e64 v153, v216, v153, s[18:19]
	v_fmac_f32_e32 v156, 0x3e38aa3b, v58
	v_cndmask_b32_e64 v156, v216, v156, s[86:87]
	v_fmac_f32_e32 v155, 0x3e38aa3b, v59
	v_cndmask_b32_e64 v155, v216, v155, s[88:89]
	v_fmac_f32_e32 v191, 0x3e38aa3b, v60
	v_cndmask_b32_e64 v191, v216, v191, s[90:91]
	v_fmac_f32_e32 v157, 0x3e38aa3b, v61
	v_cndmask_b32_e64 v157, v216, v157, s[92:93]
	v_fmac_f32_e32 v193, 0x3e38aa3b, v62
	v_cndmask_b32_e64 v193, v216, v193, s[94:95]
	v_fmac_f32_e32 v192, 0x3e38aa3b, v63
	v_cndmask_b32_e64 v192, v216, v192, s[96:97]
	v_fmac_f32_e32 v195, 0x3e38aa3b, v64
	v_cndmask_b32_e64 v195, v216, v195, s[68:69]
	v_fmac_f32_e32 v194, 0x3e38aa3b, v65
	v_cndmask_b32_e64 v194, v216, v194, s[48:49]
	v_fmac_f32_e32 v197, 0x3e38aa3b, v34
	v_cndmask_b32_e64 v197, v216, v197, s[76:77]
	v_fmac_f32_e32 v196, 0x3e38aa3b, v35
	v_cndmask_b32_e64 v196, v216, v196, s[78:79]
	v_fmac_f32_e32 v199, 0x3e38aa3b, v36
	v_cndmask_b32_e64 v199, v216, v199, s[74:75]
	v_fmac_f32_e32 v198, 0x3e38aa3b, v37
	v_cndmask_b32_e64 v198, v216, v198, s[38:39]
	v_fmac_f32_e32 v202, 0x3e38aa3b, v38
	v_cndmask_b32_e64 v202, v216, v202, s[56:57]
	v_fmac_f32_e32 v201, 0x3e38aa3b, v39
	v_cndmask_b32_e64 v201, v216, v201, s[58:59]
	v_fmac_f32_e32 v204, 0x3e38aa3b, v40
	v_cndmask_b32_e64 v204, v216, v204, s[60:61]
	v_fmac_f32_e32 v203, 0x3e38aa3b, v41
	v_cndmask_b32_e64 v203, v216, v203, s[66:67]
	v_fmac_f32_e32 v206, 0x3e38aa3b, v42
	v_cndmask_b32_e64 v206, v216, v206, s[20:21]
	v_fmac_f32_e32 v205, 0x3e38aa3b, v43
	v_cndmask_b32_e64 v205, v216, v205, s[22:23]
	v_fmac_f32_e32 v208, 0x3e38aa3b, v44
	v_cndmask_b32_e64 v208, v216, v208, s[24:25]
	v_fmac_f32_e32 v207, 0x3e38aa3b, v45
	v_cndmask_b32_e64 v207, v216, v207, s[26:27]
	v_fmac_f32_e32 v210, 0x3e38aa3b, v46
	v_cndmask_b32_e64 v210, v216, v210, s[28:29]
	v_fmac_f32_e32 v209, 0x3e38aa3b, v47
	v_cndmask_b32_e64 v209, v216, v209, s[30:31]
	v_fmac_f32_e32 v212, 0x3e38aa3b, v48
	v_cndmask_b32_e64 v212, v216, v212, s[34:35]
	v_fmac_f32_e32 v211, 0x3e38aa3b, v49
	v_cndmask_b32_e64 v211, v216, v211, s[36:37]
	s_mov_b32 s41, 0xff61b1e6
	v_max3_f32 v34, v148, s41, v0
	v_max3_f32 v34, v34, v150, v149
	v_max3_f32 v34, v34, v152, v151
	v_max3_f32 v34, v34, v154, v153
	v_max3_f32 v34, v34, v156, v155
	v_max3_f32 v34, v34, v191, v157
	v_max3_f32 v34, v34, v193, v192
	v_max3_f32 v34, v34, v195, v194
	v_max3_f32 v34, v34, v197, v196
	v_max3_f32 v34, v34, v199, v198
	v_max3_f32 v34, v34, v202, v201
	v_max3_f32 v34, v34, v204, v203
	v_max3_f32 v34, v34, v206, v205
	v_max3_f32 v34, v34, v208, v207
	v_max3_f32 v34, v34, v210, v209
	v_max3_f32 v34, v34, v212, v211
	v_mov_b32_e32 v35, v34
	s_nop 1
	v_permlane32_swap_b32_e32 v34, v35
	v_max_f32_e32 v35, v35, v35
	v_max_f32_e32 v34, v34, v34
	v_max_f32_e32 v214, v34, v35
	v_add_f32_e32 v34, 0x41000000, v146
	v_cmp_le_f32_e32 vcc, v214, v34
	v_mov_b64_e32 v[64:65], v[32:33]
	s_cmp_eq_u64 vcc, exec
	v_mov_b32_e32 v200, v146
	v_mov_b32_e32 v213, v147
	v_mov_b64_e32 v[62:63], v[30:31]
	v_mov_b64_e32 v[60:61], v[28:29]
	v_mov_b64_e32 v[58:59], v[26:27]
	v_mov_b64_e32 v[56:57], v[24:25]
	v_mov_b64_e32 v[54:55], v[22:23]
	v_mov_b64_e32 v[52:53], v[20:21]
	v_mov_b64_e32 v[50:51], v[18:19]
	v_mov_b64_e32 v[48:49], v[16:17]
	v_mov_b64_e32 v[46:47], v[14:15]
	v_mov_b64_e32 v[44:45], v[12:13]
	v_mov_b64_e32 v[42:43], v[10:11]
	v_mov_b64_e32 v[40:41], v[8:9]
	v_mov_b64_e32 v[38:39], v[6:7]
	v_mov_b64_e32 v[36:37], v[4:5]
	v_mov_b64_e32 v[34:35], v[2:3]
	s_cbranch_scc1 .LBB0_573
	v_max_f32_e32 v34, v214, v214
	v_max_f32_e32 v35, v146, v146
	v_max_f32_e32 v200, v35, v34
	v_sub_f32_e32 v34, v146, v200
	v_exp_f32_e32 v34, v34
	s_nop 0
	v_mul_f32_e32 v213, v147, v34
	v_pk_mul_f32 v[64:65], v[32:33], v[34:35] op_sel_hi:[1,0]
	v_pk_mul_f32 v[62:63], v[30:31], v[34:35] op_sel_hi:[1,0]
	v_pk_mul_f32 v[60:61], v[28:29], v[34:35] op_sel_hi:[1,0]
	v_pk_mul_f32 v[58:59], v[26:27], v[34:35] op_sel_hi:[1,0]
	v_pk_mul_f32 v[56:57], v[24:25], v[34:35] op_sel_hi:[1,0]
	v_pk_mul_f32 v[54:55], v[22:23], v[34:35] op_sel_hi:[1,0]
	v_pk_mul_f32 v[52:53], v[20:21], v[34:35] op_sel_hi:[1,0]
	v_pk_mul_f32 v[50:51], v[18:19], v[34:35] op_sel_hi:[1,0]
	v_pk_mul_f32 v[48:49], v[16:17], v[34:35] op_sel_hi:[1,0]
	v_pk_mul_f32 v[46:47], v[14:15], v[34:35] op_sel_hi:[1,0]
	v_pk_mul_f32 v[44:45], v[12:13], v[34:35] op_sel_hi:[1,0]
	v_pk_mul_f32 v[42:43], v[10:11], v[34:35] op_sel_hi:[1,0]
	v_pk_mul_f32 v[40:41], v[8:9], v[34:35] op_sel_hi:[1,0]
	v_pk_mul_f32 v[38:39], v[6:7], v[34:35] op_sel_hi:[1,0]
	v_pk_mul_f32 v[36:37], v[4:5], v[34:35] op_sel_hi:[1,0]
	v_pk_mul_f32 v[34:35], v[2:3], v[34:35] op_sel_hi:[1,0]

; #define MFMA32(a, b, c) __builtin_amdgcn_mfma_f32_32x32x16_bf16((a), (b), (c), 0, 0, 0)
; DI float xhalf_max(float v) { const auto r = __builtin_amdgcn_permlane32_swap(__float_as_uint(v), __float_as_uint(v), false, false); return fmaxf(__uint_as_float(r[0]), __uint_as_float(r[1])); }
; #define ASCHED __builtin_amdgcn_sched_barrier(0)
; template <int DV, bool LOCAL>
; DI void attn_tile(const bf16x8 (&qf)[4], const lds_u8* Kb, const lds_u8* Vb, const int (&ko)[4], const int (&vo)[4], f32x16 (&o)[DV / 32], float& m, float& l, int hh,
;                   const float* rpbs, int drow, int cq, int c0) {
;     ...
;   f32x16 st[2];
;   {
;     bf16x8 kf[2][4];
; #pragma unroll
;     for (int t = 0; t < 2; ++t)
; #pragma unroll
;       for (int ks = 0; ks < 4; ++ks) kf[t][ks] = *(const lds_bf16x8*)(Kb + ko[ks] + t * 4096);
;     ASCHED;
; #pragma unroll
;     for (int t = 0; t < 2; ++t) {
;       f32x16 s;
; #pragma unroll
;       for (int i = 0; i < 16; ++i) s[i] = 0.f;
; #pragma unroll
;       for (int ks = 0; ks < 4; ++ks) s = MFMA32(kf[t][ks], qf[ks], s);
;       st[t] = s;
;     }
;   }
;   bf16x8 va[2][ND];
; #pragma unroll
;   for (int s2 = 0; s2 < 2; ++s2)
; #pragma unroll
;     for (int d = 0; d < ND; ++d) va[s2][d] = *(const lds_bf16x8*)(Vb + vo[s2] + d * 4096);
;   ASCHED;
;   float mx = -3.0e38f;
;   if (LOCAL) {
; #pragma unroll
;     for (int t = 0; t < 2; ++t)
; #pragma unroll
;       for (int i = 0; i < 16; ++i) {
;         const int ck = 32 * t + 16 * (i >> 3) + 8 * hh + (i & 7);
;         const int dc = ck - cq + 15;
;         const bool ok = (ck >= c0) && (ck < c0 + 16);
;         const int dcc = dc < 0 ? 0 : (dc > 30 ? 30 : dc);
;         const float z = ok ? __builtin_fmaf(st[t][i], QK_C, rpbs[drow * 31 + dcc]) : -1.0e30f;
;         st[t][i] = z; mx = fmaxf(mx, z);
;       }
;   } else {
; #pragma unroll
;     for (int t = 0; t < 2; ++t)
; #pragma unroll
;       for (int i = 0; i < 16; ++i) mx = fmaxf(mx, st[t][i]);
;     mx *= QK_C;
;   }
;   mx = xhalf_max(mx);
;   if (!__all(mx <= m + 8.0f)) {
;     const float mn = fmaxf(m, mx);
;     const float alpha = __builtin_amdgcn_exp2f(m - mn);
;     m = mn; l *= alpha;
; #pragma unroll
;     for (int d = 0; d < ND; ++d) o[d] *= alpha;
;   }
.LBB0_580:
	v_add_u32_e32 v0, s55, v99
	s_nop 6
	v_add_u32_e32 v46, s55, v101
	s_nop 0
	v_add_u32_e32 v50, s55, v106
	v_add_u32_e32 v51, s55, v107
	ds_read_b128 v[34:37], v0
	ds_read_b128 v[38:41], v0 offset:4096
	ds_read_b128 v[42:45], v46
	ds_read_b128 v[82:85], v46 offset:4096
	ds_read_b128 v[46:49], v50
	ds_read_b128 v[86:89], v50 offset:4096
	ds_read_b128 v[90:93], v51
	ds_read_b128 v[94:97], v51 offset:4096
	s_waitcnt lgkmcnt(0)
	v_mfma_f32_32x32x16_bf16 v[50:65], v[34:37], v[74:77], 0
	v_add_u32_e32 v0, s55, v108
	v_mfma_f32_32x32x16_bf16 v[50:65], v[42:45], v[66:69], v[50:65]
	v_mfma_f32_32x32x16_bf16 v[50:65], v[46:49], v[70:73], v[50:65]
	v_mfma_f32_32x32x16_bf16 v[34:49], v[38:41], v[74:77], 0
	v_mfma_f32_32x32x16_bf16 v[34:49], v[82:85], v[66:69], v[34:49]
	v_mfma_f32_32x32x16_bf16 v[34:49], v[86:89], v[70:73], v[34:49]
	v_mfma_f32_32x32x16_bf16 v[50:65], v[90:93], v[78:81], v[50:65]
	v_mfma_f32_32x32x16_bf16 v[34:49], v[94:97], v[78:81], v[34:49]
	ds_read_b128 v[94:97], v0 offset:8192
	ds_read_b128 v[90:93], v0 offset:12288
	v_add_u32_e32 v0, s55, v109
	ds_read_b128 v[86:89], v0 offset:8192
	ds_read_b128 v[82:85], v0 offset:12288
	s_mov_b32 s41, 0xff61b1e6
	s_nop 4
	v_max3_f32 v0, v50, s41, v51
	v_max3_f32 v0, v0, v52, v53
	v_max3_f32 v0, v0, v54, v55
	v_max3_f32 v0, v0, v56, v57
	v_max3_f32 v0, v0, v58, v59
	v_max3_f32 v0, v0, v60, v61
	v_max3_f32 v0, v0, v62, v63
	v_max3_f32 v0, v0, v64, v65
	v_max3_f32 v0, v0, v34, v35
	v_max3_f32 v0, v0, v36, v37
	v_max3_f32 v0, v0, v38, v39
	v_max3_f32 v0, v0, v40, v41
	v_max3_f32 v0, v0, v42, v43
	v_max3_f32 v0, v0, v44, v45
	v_max3_f32 v0, v0, v46, v47
	v_max3_f32 v0, v0, v48, v49
	v_mul_f32_e32 v0, 0x3e38aa3b, v0
	v_mov_b32_e32 v148, v0
	s_nop 1
	v_permlane32_swap_b32_e32 v0, v148
	v_max_f32_e32 v148, v148, v148
	v_max_f32_e32 v0, v0, v0
	v_max_f32_e32 v0, v0, v148
	v_add_f32_e32 v148, 0x41000000, v146
	v_cmp_le_f32_e32 vcc, v0, v148
	s_cmp_eq_u64 vcc, exec
	s_cbranch_scc1 .LBB0_582
	v_max_f32_e32 v0, v0, v0
	v_max_f32_e32 v148, v146, v146
	v_max_f32_e32 v148, v148, v0
	v_sub_f32_e32 v0, v146, v148
	v_exp_f32_e32 v0, v0
	v_mov_b32_e32 v146, v148
	v_mul_f32_e32 v147, v147, v0
	v_pk_mul_f32 v[32:33], v[32:33], v[0:1] op_sel_hi:[1,0]
	v_pk_mul_f32 v[30:31], v[30:31], v[0:1] op_sel_hi:[1,0]
	v_pk_mul_f32 v[28:29], v[28:29], v[0:1] op_sel_hi:[1,0]
	v_pk_mul_f32 v[26:27], v[26:27], v[0:1] op_sel_hi:[1,0]
	v_pk_mul_f32 v[24:25], v[24:25], v[0:1] op_sel_hi:[1,0]
	v_pk_mul_f32 v[22:23], v[22:23], v[0:1] op_sel_hi:[1,0]
	v_pk_mul_f32 v[20:21], v[20:21], v[0:1] op_sel_hi:[1,0]
	v_pk_mul_f32 v[18:19], v[18:19], v[0:1] op_sel_hi:[1,0]
	v_pk_mul_f32 v[16:17], v[16:17], v[0:1] op_sel_hi:[1,0]
	v_pk_mul_f32 v[14:15], v[14:15], v[0:1] op_sel_hi:[1,0]
	v_pk_mul_f32 v[12:13], v[12:13], v[0:1] op_sel_hi:[1,0]
	v_pk_mul_f32 v[10:11], v[10:11], v[0:1] op_sel_hi:[1,0]
	v_pk_mul_f32 v[8:9], v[8:9], v[0:1] op_sel_hi:[1,0]
	v_pk_mul_f32 v[6:7], v[6:7], v[0:1] op_sel_hi:[1,0]
	v_pk_mul_f32 v[4:5], v[4:5], v[0:1] op_sel_hi:[1,0]
	v_pk_mul_f32 v[2:3], v[2:3], v[0:1] op_sel_hi:[1,0]

; template <int MODE, int CH = -1>
; DI void lru_group_unit(KP p, int l, int g, int n, char* ldsc) {
;     ...
;   __syncthreads();
;   {
;     const bf16_t* Wg = p->Wl + (size_t)((l * 4 + n) * 4) * 4096;
; #pragma unroll
;     for (int u = 0; u < 4; ++u) { const int q = tid + NT * u, rowi = q >> 3, pc = q & 7;
;       *(u32x4*)(Wn + rowi * 72 + pc * 8) = *(const u32x4*)(Wg + rowi * 64 + pc * 8); }
;     if (tid < 128) { const int dir = tid >> 6, ch = tid & 63, gch = (l * 2 + dir) * 256 + n * 64 + ch;
;       cst[tid * 3 + 0] = p->lru_ba[gch]; cst[tid * 3 + 1] = p->lru_bx[gch]; cst[tid * 3 + 2] = -8.0f * log1pf(expf(-p->lru_lam[gch])); }
.LBB0_587:
	v_mov_b32_e32 v44, v158
	s_waitcnt vmcnt(0) lgkmcnt(0)
	s_barrier
	s_load_dwordx2 s[2:3], s[80:81], 0xe0
	s_and_b32 s0, s29, 3
	s_lshl_b32 s1, s0, 15
	s_or_b32 s1, s1, s26
	v_lshlrev_b32_e32 v0, 4, v44
	s_waitcnt lgkmcnt(0)
	s_add_u32 s2, s2, s1
	v_ashrrev_i32_e32 v9, 3, v44
	s_addc_u32 s3, s3, 0
	v_and_b32_e32 v0, 0x70, v0
	v_lshlrev_b32_e32 v2, 6, v9
	v_lshl_add_u64 v[6:7], s[2:3], 0, v[0:1]
	v_add_u32_e32 v252, 0x200, v44
	v_ashrrev_i32_e32 v252, 3, v252
	v_lshlrev_b32_e32 v252, 6, v252
	v_ashrrev_i32_e32 v253, 31, v252
	v_lshl_add_u64 v[252:253], v[252:253], 1, v[6:7]
	global_load_dwordx4 v[244:247], v[252:253], off
	v_add_u32_e32 v252, 0x400, v44
	v_ashrrev_i32_e32 v252, 3, v252
	v_lshlrev_b32_e32 v252, 6, v252
	v_ashrrev_i32_e32 v253, 31, v252
	v_lshl_add_u64 v[252:253], v[252:253], 1, v[6:7]
	global_load_dwordx4 v[244:247], v[252:253], off
	v_add_u32_e32 v252, 0x600, v44
	v_ashrrev_i32_e32 v252, 3, v252
	v_lshlrev_b32_e32 v252, 6, v252
	v_ashrrev_i32_e32 v253, 31, v252
	v_lshl_add_u64 v[252:253], v[252:253], 1, v[6:7]
	global_load_dwordx4 v[244:247], v[252:253], off
	v_ashrrev_i32_e32 v3, 31, v2
	v_lshl_add_u64 v[2:3], v[2:3], 1, v[6:7]
	global_load_dwordx4 v[2:5], v[2:3], off
	v_add_u32_e32 v8, 0, v0
	v_mad_u64_u32 v[10:11], s[2:3], v9, s79, v[8:9]
	v_ashrrev_i32_e32 v22, 6, v44
	v_cmp_gt_i32_e32 vcc, s78, v44
	v_readfirstlane_b32 s30, v22
	v_cmp_lt_i32_e64 s[4:5], s86, v44
	s_waitcnt vmcnt(0)
	ds_write_b128 v10, v[2:5]
	v_add_u32_e32 v2, 0x200, v44
	v_ashrrev_i32_e32 v9, 3, v2
	v_lshlrev_b32_e32 v2, 6, v9
	v_ashrrev_i32_e32 v3, 31, v2
	v_lshl_add_u64 v[2:3], v[2:3], 1, v[6:7]
	global_load_dwordx4 v[2:5], v[2:3], off
	v_mad_u64_u32 v[10:11], s[2:3], v9, s79, v[8:9]
	s_waitcnt vmcnt(0)
	ds_write_b128 v10, v[2:5]
	v_add_u32_e32 v2, 0x400, v44
	v_ashrrev_i32_e32 v9, 3, v2
	v_lshlrev_b32_e32 v2, 6, v9
	v_ashrrev_i32_e32 v3, 31, v2
	v_lshl_add_u64 v[2:3], v[2:3], 1, v[6:7]
	global_load_dwordx4 v[2:5], v[2:3], off
	v_mad_u64_u32 v[10:11], s[2:3], v9, s79, v[8:9]
	s_waitcnt vmcnt(0)
	ds_write_b128 v10, v[2:5]
	v_add_u32_e32 v2, 0x600, v44
	v_ashrrev_i32_e32 v9, 3, v2
	v_lshlrev_b32_e32 v2, 6, v9
	v_ashrrev_i32_e32 v3, 31, v2
	v_lshl_add_u64 v[2:3], v[2:3], 1, v[6:7]
	global_load_dwordx4 v[2:5], v[2:3], off
	v_mad_u64_u32 v[6:7], s[2:3], v9, s79, v[8:9]
	s_waitcnt vmcnt(0)
	ds_write_b128 v6, v[2:5]
	s_and_saveexec_b64 s[2:3], s[4:5]
	s_xor_b64 s[4:5], exec, s[2:3]
	s_lshl_b32 s1, s0, 6
	s_or_saveexec_b64 s[6:7], s[4:5]
	v_and_b32_e32 v45, 63, v44
	v_mov_b32_e32 v38, s1
	s_xor_b64 exec, exec, s[6:7]
	s_cbranch_execz .LBB0_591
	s_load_dwordx4 s[8:11], s[80:81], 0x70
	v_lshl_add_u32 v2, v22, 8, s27
	s_lshl_b32 s0, s0, 6
	v_or3_b32 v2, v2, s0, v45
	v_ashrrev_i32_e32 v3, 31, v2
	v_lshlrev_b64 v[2:3], 2, v[2:3]
	s_waitcnt lgkmcnt(0)
	v_lshl_add_u64 v[4:5], s[10:11], 0, v[2:3]
	global_load_dword v6, v[4:5], off
	s_load_dwordx2 s[2:3], s[80:81], 0x60
	v_mov_b32_e32 v38, s0
	s_waitcnt lgkmcnt(0)
	v_lshl_add_u64 v[4:5], s[2:3], 0, v[2:3]
	v_lshl_add_u64 v[2:3], s[8:9], 0, v[2:3]
	global_load_dword v4, v[4:5], off
	s_nop 0
	global_load_dword v5, v[2:3], off
	v_mov_b32_e32 v2, v1
	s_waitcnt vmcnt(2)
	v_mul_f32_e32 v3, 0xbfb8aa3b, v6
	v_fma_f32 v7, v6, s87, -v3
	v_rndne_f32_e32 v8, v3
	v_fmac_f32_e32 v7, 0xb2a5705f, v6
	v_sub_f32_e32 v3, v3, v8
	v_add_f32_e32 v3, v3, v7
	v_cvt_i32_f32_e32 v8, v8
	v_exp_f32_e32 v7, v3
	v_mad_u64_u32 v[2:3], s[2:3], v44, 12, v[2:3]
	v_add_u32_e32 v3, 0x9000, v2
	s_waitcnt vmcnt(0)
	ds_write2_b32 v3, v4, v5 offset1:1
	v_ldexp_f32 v3, v7, v8
	v_cmp_nlt_f32_e64 s[4:5], s88, v6
	s_nop 1
	v_cndmask_b32_e64 v3, 0, v3, s[4:5]
	v_cmp_ngt_f32_e64 s[4:5], s89, v6
	s_nop 1
	v_cndmask_b32_e64 v3, v177, v3, s[4:5]
	v_add_f32_e32 v6, 1.0, v3
	v_add_f32_e32 v7, -1.0, v6
	v_frexp_mant_f32_e32 v8, v6
	v_cvt_f64_f32_e32 v[4:5], v6
	v_sub_f32_e32 v9, v7, v6
	v_frexp_exp_i32_f64_e32 v4, v[4:5]
	v_cmp_gt_f32_e64 s[4:5], s91, v8
	v_sub_f32_e32 v7, v3, v7
	v_add_f32_e32 v5, 1.0, v9
	v_subbrev_co_u32_e64 v4, s[4:5], 0, v4, s[4:5]
	v_add_f32_e32 v5, v7, v5
	v_sub_u32_e32 v7, 0, v4
	v_cvt_f32_i32_e32 v4, v4
	v_ldexp_f32 v6, v6, v7
	v_ldexp_f32 v5, v5, v7
	v_add_f32_e32 v7, -1.0, v6
	v_add_f32_e32 v8, 1.0, v6
	v_add_f32_e32 v9, 1.0, v7
	v_add_f32_e32 v10, -1.0, v8
	v_sub_f32_e32 v9, v6, v9
	v_sub_f32_e32 v6, v6, v10
	v_mul_f32_e32 v10, 0x3f317218, v4
	v_add_f32_e32 v9, v5, v9
	v_add_f32_e32 v5, v5, v6
	v_fma_f32 v6, v4, s92, -v10
	v_add_f32_e32 v11, v7, v9
	v_add_f32_e32 v12, v8, v5
	v_fmac_f32_e32 v6, 0xb102e308, v4
	v_sub_f32_e32 v4, v7, v11
	v_sub_f32_e32 v7, v8, v12
	v_rcp_f32_e32 v8, v12
	v_add_f32_e32 v13, v10, v6
	v_add_f32_e32 v5, v5, v7
	v_sub_f32_e32 v7, v13, v10
	v_sub_f32_e32 v6, v6, v7
	v_mul_f32_e32 v7, v11, v8
	v_add_f32_e32 v4, v9, v4
	v_mul_f32_e32 v9, v12, v7
	v_fma_f32 v10, v7, v12, -v9
	v_fmac_f32_e32 v10, v7, v5
	v_add_f32_e32 v14, v9, v10
	v_sub_f32_e32 v15, v11, v14
	v_sub_f32_e32 v9, v14, v9
	v_sub_f32_e32 v11, v11, v15
	v_sub_f32_e32 v9, v9, v10
	v_sub_f32_e32 v10, v11, v14
	v_add_f32_e32 v4, v4, v10
	v_add_f32_e32 v4, v9, v4
	v_add_f32_e32 v9, v15, v4
	v_mul_f32_e32 v10, v8, v9
	v_sub_f32_e32 v11, v15, v9
	v_mul_f32_e32 v14, v12, v10
	v_add_f32_e32 v4, v4, v11
	v_add_f32_e32 v11, v7, v10
	v_fma_f32 v12, v10, v12, -v14
	v_sub_f32_e32 v7, v11, v7
	v_fmac_f32_e32 v12, v10, v5
	v_sub_f32_e32 v5, v10, v7
	v_add_f32_e32 v7, v14, v12
	v_sub_f32_e32 v10, v7, v14
	v_sub_f32_e32 v14, v9, v7
	v_sub_f32_e32 v9, v9, v14
	v_sub_f32_e32 v7, v9, v7
	v_sub_f32_e32 v10, v10, v12
	v_add_f32_e32 v4, v4, v7
	v_add_f32_e32 v4, v10, v4
	v_add_f32_e32 v4, v14, v4
	v_mul_f32_e32 v4, v8, v4
	v_add_f32_e32 v4, v5, v4
	v_add_f32_e32 v5, v11, v4
	v_mul_f32_e32 v7, v5, v5
	v_fmamk_f32 v10, v7, 0x3e9b6dac, v167
	v_sub_f32_e32 v8, v5, v11
	v_ldexp_f32 v9, v5, 1
	v_mul_f32_e32 v5, v5, v7
	v_fmaak_f32 v7, v7, v10, 0x3f2aaada
	v_mul_f32_e32 v5, v5, v7
	v_add_f32_e32 v7, v9, v5
	v_sub_f32_e32 v4, v4, v8
	v_sub_f32_e32 v8, v7, v9
	v_ldexp_f32 v4, v4, 1
	v_sub_f32_e32 v5, v5, v8
	v_add_f32_e32 v4, v4, v5
	v_add_f32_e32 v5, v7, v4
	v_sub_f32_e32 v7, v5, v7
	v_add_f32_e32 v8, v13, v5
	v_sub_f32_e32 v4, v4, v7
	v_sub_f32_e32 v7, v8, v13
	v_sub_f32_e32 v9, v8, v7
	v_sub_f32_e32 v5, v5, v7
	v_add_f32_e32 v7, v6, v4
	v_sub_f32_e32 v9, v13, v9
	v_sub_f32_e32 v10, v7, v6
	v_add_f32_e32 v5, v5, v9
	v_sub_f32_e32 v9, v7, v10
	v_sub_f32_e32 v4, v4, v10
	v_sub_f32_e32 v6, v6, v9
	v_add_f32_e32 v5, v7, v5
	v_add_f32_e32 v4, v4, v6
	v_add_f32_e32 v6, v8, v5
	v_sub_f32_e32 v7, v6, v8
	v_sub_f32_e32 v5, v5, v7
	v_add_f32_e32 v4, v4, v5
	v_add_f32_e32 v4, v6, v4
	v_cmp_neq_f32_e64 s[4:5], s90, v3
	s_nop 1
	v_cndmask_b32_e64 v4, v177, v4, s[4:5]
	v_cmp_lt_f32_e64 s[4:5], |v3|, s93
	s_nop 1
	v_cndmask_b32_e64 v3, v4, v3, s[4:5]
	v_mul_f32_e32 v3, 0xc1000000, v3
	ds_write_b32 v2, v3 offset:36872
; template <int MODE, int CH = -1>
; DI void lru_group_unit(KP p, int l, int g, int n, char* ldsc) {
;     ...
;     for (int q = lane; q < 35 * 8; q += 64) {
;       const int tt = q >> 3, pc = q & 7, t = t0 + tt - 2;
;       u32x4 v = {0u, 0u, 0u, 0u};
;       if (t >= 0 && t < L) v = *(const u32x4*)(p->P + (size_t)(row0 + tt - 2) * INC + n * 64 + pc * 8);
;       *(u32x4*)(xs + tt * 64 + pc * 8) = v;
;     }
.LBB0_591:
	s_or_b64 exec, exec, s[6:7]
	v_mov_b32_e32 v39, v1
	s_ashr_i32 s34, s29, 2
	v_lshl_add_u64 v[2:3], v[38:39], 1, s[40:41]
	s_and_b32 s1, s34, 31
	v_lshl_add_u64 v[6:7], v[2:3], 0, v[0:1]
	v_lshrrev_b32_e32 v2, 3, v45
	s_mul_i32 s0, s30, 0x2400
	s_lshl_b32 s2, s34, 8
	s_lshl_b32 s3, s30, 5
	s_lshl_b32 s4, s1, 8
	v_add_u32_e32 v3, -2, v2
	v_lshlrev_b32_e32 v2, 7, v2
	s_add_i32 s31, s3, s2
	v_or3_b32 v0, s0, v2, v0
	s_add_i32 s3, s3, s4
	v_lshlrev_b32_e32 v23, 3, v44
	v_or_b32_e32 v8, 0xffffffc0, v45
	v_add_u32_e32 v9, s31, v3
	v_add_u32_e32 v0, s94, v0
	v_add_u32_e32 v10, s3, v3
	s_mov_b64 s[6:7], 0
	v_mad_i64_i32 v[252:253], s[2:3], v9, s45, v[6:7]
	global_load_dwordx4 v[248:251], v[252:253], off
	v_add_u32_e32 v244, 8, v9
	v_mad_i64_i32 v[252:253], s[2:3], v244, s45, v[6:7]
	global_load_dwordx4 v[248:251], v[252:253], off
	v_add_u32_e32 v244, 16, v9
	v_mad_i64_i32 v[252:253], s[2:3], v244, s45, v[6:7]
	global_load_dwordx4 v[248:251], v[252:253], off
	v_add_u32_e32 v244, 24, v9
	v_mad_i64_i32 v[252:253], s[2:3], v244, s45, v[6:7]
	global_load_dwordx4 v[248:251], v[252:253], off
	v_add_u32_e32 v244, 32, v9
	v_mad_i64_i32 v[252:253], s[2:3], v244, s45, v[6:7]
	global_load_dwordx4 v[248:251], v[252:253], off
	s_branch .LBB0_593
